# S5 carry pass rewritten by hand: the 132-chunk chain of a (dir,batch,group) is split over the 8 waves of a workgroup, segment totals combined through LDS
# speedup vs baseline: 1.0034x; 1.0034x over previous
.LBB0_590:
	s_cmp_lt_i32 s90, 8
	s_cselect_b64 s[0:1], -1, 0
	s_and_b64 s[2:3], s[0:1], s[2:3]
	s_andn2_b64 vcc, exec, s[2:3]
	s_cbranch_vccnz .LBB0_596
	s_cmpk_gt_u32 s8, 0xff
	s_cbranch_scc1 .Lp7_done
	s_mov_b32 s4, s8
	v_lshlrev_b32_e32 v0, 3, v176
	s_mul_i32 s20, s95, 17
	s_movk_i32 s22, 17
	s_cmp_lt_u32 s95, 4
	s_cbranch_scc1 .Lp7_seg
	s_lshl_b32 s20, s95, 4
	s_add_i32 s20, s20, 4
	s_movk_i32 s22, 16
.Lp7_seg:
.Lp7_chain:
	s_lshr_b32 s5, s4, 7
	s_bfe_u32 s6, s4, 0x10006
	s_and_b32 s7, s4, 63
	s_lshl_b32 s10, s5, 1
	s_add_i32 s10, s10, s6
	s_mul_i32 s10, s10, 0x420000
	s_lshl_b32 s11, s7, 9
	s_add_i32 s10, s10, s11
	s_add_u32 s12, s30, 0xf700000
	s_addc_u32 s13, s31, 0
	s_add_u32 s12, s12, s10
	s_addc_u32 s13, s13, 0
	s_add_u32 s14, s30, 0x10800000
	s_addc_u32 s15, s31, 0
	s_add_u32 s14, s14, s10
	s_addc_u32 s15, s15, 0
	s_lshl_b32 s10, s5, 6
	s_add_i32 s10, s10, s7
	s_lshl_b32 s10, s10, 9
	s_add_u32 s44, s30, 0x50000
	s_addc_u32 s45, s31, 0
	s_add_u32 s44, s44, s10
	s_addc_u32 s45, s45, 0
	global_load_dwordx2 v[2:3], v0, s[44:45]
	s_add_i32 s25, s20, 0
	s_cmp_eq_u32 s5, 0
	s_cbranch_scc1 .Lp7_c0
	s_sub_i32 s27, 3, s25
	s_sub_i32 s10, 0x87, s25
	s_cmp_lt_u32 s25, 4
	s_cselect_b32 s27, s27, s10
	s_branch .Lp7_d0
.Lp7_c0:
	s_mov_b32 s27, s25
.Lp7_d0:
	s_lshl_b32 s10, s27, 15
	s_add_u32 s46, s12, s10
	s_addc_u32 s47, s13, 0
	global_load_dwordx2 v[20:21], v0, s[46:47]
	s_add_i32 s25, s20, 1
	s_cmp_eq_u32 s5, 0
	s_cbranch_scc1 .Lp7_c1
	s_sub_i32 s27, 3, s25
	s_sub_i32 s10, 0x87, s25
	s_cmp_lt_u32 s25, 4
	s_cselect_b32 s27, s27, s10
	s_branch .Lp7_d1

.Lp7_d1:
	s_lshl_b32 s10, s27, 15
	s_add_u32 s46, s12, s10
	s_addc_u32 s47, s13, 0
	global_load_dwordx2 v[22:23], v0, s[46:47]
	s_add_i32 s25, s20, 2
	s_cmp_eq_u32 s5, 0
	s_cbranch_scc1 .Lp7_c2
	s_sub_i32 s27, 3, s25
	s_sub_i32 s10, 0x87, s25
	s_cmp_lt_u32 s25, 4
	s_cselect_b32 s27, s27, s10
	s_branch .Lp7_d2

.Lp7_d2:
	s_lshl_b32 s10, s27, 15
	s_add_u32 s46, s12, s10
	s_addc_u32 s47, s13, 0
	global_load_dwordx2 v[24:25], v0, s[46:47]
	s_add_i32 s25, s20, 3
	s_cmp_eq_u32 s5, 0
	s_cbranch_scc1 .Lp7_c3
	s_sub_i32 s27, 3, s25
	s_sub_i32 s10, 0x87, s25
	s_cmp_lt_u32 s25, 4
	s_cselect_b32 s27, s27, s10
	s_branch .Lp7_d3

.Lp7_d3:
	s_lshl_b32 s10, s27, 15
	s_add_u32 s46, s12, s10
	s_addc_u32 s47, s13, 0
	global_load_dwordx2 v[26:27], v0, s[46:47]
	s_add_i32 s25, s20, 4
	s_cmp_eq_u32 s5, 0
	s_cbranch_scc1 .Lp7_c4
	s_sub_i32 s27, 3, s25
	s_sub_i32 s10, 0x87, s25
	s_cmp_lt_u32 s25, 4
	s_cselect_b32 s27, s27, s10
	s_branch .Lp7_d4

.Lp7_d4:
	s_lshl_b32 s10, s27, 15
	s_add_u32 s46, s12, s10
	s_addc_u32 s47, s13, 0
	global_load_dwordx2 v[28:29], v0, s[46:47]
	s_add_i32 s25, s20, 5
	s_cmp_eq_u32 s5, 0
	s_cbranch_scc1 .Lp7_c5
	s_sub_i32 s27, 3, s25
	s_sub_i32 s10, 0x87, s25
	s_cmp_lt_u32 s25, 4
	s_cselect_b32 s27, s27, s10
	s_branch .Lp7_d5

.Lp7_d5:
	s_lshl_b32 s10, s27, 15
	s_add_u32 s46, s12, s10
	s_addc_u32 s47, s13, 0
	global_load_dwordx2 v[30:31], v0, s[46:47]
	s_add_i32 s25, s20, 6
	s_cmp_eq_u32 s5, 0
	s_cbranch_scc1 .Lp7_c6
	s_sub_i32 s27, 3, s25
	s_sub_i32 s10, 0x87, s25
	s_cmp_lt_u32 s25, 4
	s_cselect_b32 s27, s27, s10
	s_branch .Lp7_d6

.Lp7_d6:
	s_lshl_b32 s10, s27, 15
	s_add_u32 s46, s12, s10
	s_addc_u32 s47, s13, 0
	global_load_dwordx2 v[32:33], v0, s[46:47]
	s_add_i32 s25, s20, 7
	s_cmp_eq_u32 s5, 0
	s_cbranch_scc1 .Lp7_c7
	s_sub_i32 s27, 3, s25
	s_sub_i32 s10, 0x87, s25
	s_cmp_lt_u32 s25, 4
	s_cselect_b32 s27, s27, s10
	s_branch .Lp7_d7

.Lp7_d7:
	s_lshl_b32 s10, s27, 15
	s_add_u32 s46, s12, s10
	s_addc_u32 s47, s13, 0
	global_load_dwordx2 v[34:35], v0, s[46:47]
	s_add_i32 s25, s20, 8
	s_cmp_eq_u32 s5, 0
	s_cbranch_scc1 .Lp7_c8
	s_sub_i32 s27, 3, s25
	s_sub_i32 s10, 0x87, s25
	s_cmp_lt_u32 s25, 4
	s_cselect_b32 s27, s27, s10
	s_branch .Lp7_d8

.Lp7_d8:
	s_lshl_b32 s10, s27, 15
	s_add_u32 s46, s12, s10
	s_addc_u32 s47, s13, 0
	global_load_dwordx2 v[36:37], v0, s[46:47]
	s_add_i32 s25, s20, 9
	s_cmp_eq_u32 s5, 0
	s_cbranch_scc1 .Lp7_c9
	s_sub_i32 s27, 3, s25
	s_sub_i32 s10, 0x87, s25
	s_cmp_lt_u32 s25, 4
	s_cselect_b32 s27, s27, s10
	s_branch .Lp7_d9

.Lp7_d9:
	s_lshl_b32 s10, s27, 15
	s_add_u32 s46, s12, s10
	s_addc_u32 s47, s13, 0
	global_load_dwordx2 v[38:39], v0, s[46:47]
	s_add_i32 s25, s20, 10
	s_cmp_eq_u32 s5, 0
	s_cbranch_scc1 .Lp7_c10
	s_sub_i32 s27, 3, s25
	s_sub_i32 s10, 0x87, s25
	s_cmp_lt_u32 s25, 4
	s_cselect_b32 s27, s27, s10
	s_branch .Lp7_d10

.Lp7_d10:
	s_lshl_b32 s10, s27, 15
	s_add_u32 s46, s12, s10
	s_addc_u32 s47, s13, 0
	global_load_dwordx2 v[40:41], v0, s[46:47]
	s_add_i32 s25, s20, 11
	s_cmp_eq_u32 s5, 0
	s_cbranch_scc1 .Lp7_c11
	s_sub_i32 s27, 3, s25
	s_sub_i32 s10, 0x87, s25
	s_cmp_lt_u32 s25, 4
	s_cselect_b32 s27, s27, s10
	s_branch .Lp7_d11

.Lp7_d11:
	s_lshl_b32 s10, s27, 15
	s_add_u32 s46, s12, s10
	s_addc_u32 s47, s13, 0
	global_load_dwordx2 v[42:43], v0, s[46:47]
	s_add_i32 s25, s20, 12
	s_cmp_eq_u32 s5, 0
	s_cbranch_scc1 .Lp7_c12
	s_sub_i32 s27, 3, s25
	s_sub_i32 s10, 0x87, s25
	s_cmp_lt_u32 s25, 4
	s_cselect_b32 s27, s27, s10
	s_branch .Lp7_d12

.Lp7_d12:
	s_lshl_b32 s10, s27, 15
	s_add_u32 s46, s12, s10
	s_addc_u32 s47, s13, 0
	global_load_dwordx2 v[44:45], v0, s[46:47]
	s_add_i32 s25, s20, 13
	s_cmp_eq_u32 s5, 0
	s_cbranch_scc1 .Lp7_c13
	s_sub_i32 s27, 3, s25
	s_sub_i32 s10, 0x87, s25
	s_cmp_lt_u32 s25, 4
	s_cselect_b32 s27, s27, s10
	s_branch .Lp7_d13

.Lp7_d13:
	s_lshl_b32 s10, s27, 15
	s_add_u32 s46, s12, s10
	s_addc_u32 s47, s13, 0
	global_load_dwordx2 v[46:47], v0, s[46:47]
	s_add_i32 s25, s20, 14
	s_cmp_eq_u32 s5, 0
	s_cbranch_scc1 .Lp7_c14
	s_sub_i32 s27, 3, s25
	s_sub_i32 s10, 0x87, s25
	s_cmp_lt_u32 s25, 4
	s_cselect_b32 s27, s27, s10
	s_branch .Lp7_d14

.Lp7_d14:
	s_lshl_b32 s10, s27, 15
	s_add_u32 s46, s12, s10
	s_addc_u32 s47, s13, 0
	global_load_dwordx2 v[48:49], v0, s[46:47]
	s_add_i32 s25, s20, 15
	s_cmp_eq_u32 s5, 0
	s_cbranch_scc1 .Lp7_c15
	s_sub_i32 s27, 3, s25
	s_sub_i32 s10, 0x87, s25
	s_cmp_lt_u32 s25, 4
	s_cselect_b32 s27, s27, s10
	s_branch .Lp7_d15

.Lp7_d15:
	s_lshl_b32 s10, s27, 15
	s_add_u32 s46, s12, s10
	s_addc_u32 s47, s13, 0
	global_load_dwordx2 v[50:51], v0, s[46:47]
	s_cmp_eq_u32 s22, 16
	s_cbranch_scc1 .Lp7_ld_done
	s_add_i32 s25, s20, 16
	s_cmp_eq_u32 s5, 0
	s_cbranch_scc1 .Lp7_c16
	s_sub_i32 s27, 3, s25
	s_sub_i32 s10, 0x87, s25
	s_cmp_lt_u32 s25, 4
	s_cselect_b32 s27, s27, s10
	s_branch .Lp7_d16

.Lp7_d16:
	s_lshl_b32 s10, s27, 15
	s_add_u32 s46, s12, s10
	s_addc_u32 s47, s13, 0
	global_load_dwordx2 v[52:53], v0, s[46:47]
.Lp7_ld_done:
	s_waitcnt vmcnt(0)
	v_mov_b32_e32 v4, 0
	v_mov_b32_e32 v5, 0
	v_mov_b32_e32 v54, v4
	v_mov_b32_e32 v55, v5
	v_fma_f32 v6, v2, v4, v20
	v_fma_f32 v7, v2, v5, v21
	v_fma_f32 v6, -v3, v55, v6
	v_fma_f32 v7, v3, v54, v7
	v_mov_b32_e32 v4, v6
	v_mov_b32_e32 v5, v7
	v_mov_b32_e32 v56, v4
	v_mov_b32_e32 v57, v5
	v_fma_f32 v6, v2, v4, v22
	v_fma_f32 v7, v2, v5, v23
	v_fma_f32 v6, -v3, v57, v6
	v_fma_f32 v7, v3, v56, v7
	v_mov_b32_e32 v4, v6
	v_mov_b32_e32 v5, v7
	v_mov_b32_e32 v58, v4
	v_mov_b32_e32 v59, v5
	v_fma_f32 v6, v2, v4, v24
	v_fma_f32 v7, v2, v5, v25
	v_fma_f32 v6, -v3, v59, v6
	v_fma_f32 v7, v3, v58, v7
	v_mov_b32_e32 v4, v6
	v_mov_b32_e32 v5, v7
	v_mov_b32_e32 v60, v4
	v_mov_b32_e32 v61, v5
	v_fma_f32 v6, v2, v4, v26
	v_fma_f32 v7, v2, v5, v27
	v_fma_f32 v6, -v3, v61, v6
	v_fma_f32 v7, v3, v60, v7
	v_mov_b32_e32 v4, v6
	v_mov_b32_e32 v5, v7
	v_mov_b32_e32 v62, v4
	v_mov_b32_e32 v63, v5
	v_fma_f32 v6, v2, v4, v28
	v_fma_f32 v7, v2, v5, v29
	v_fma_f32 v6, -v3, v63, v6
	v_fma_f32 v7, v3, v62, v7
	v_mov_b32_e32 v4, v6
	v_mov_b32_e32 v5, v7
	v_mov_b32_e32 v64, v4
	v_mov_b32_e32 v65, v5
	v_fma_f32 v6, v2, v4, v30
	v_fma_f32 v7, v2, v5, v31
	v_fma_f32 v6, -v3, v65, v6
	v_fma_f32 v7, v3, v64, v7
	v_mov_b32_e32 v4, v6
	v_mov_b32_e32 v5, v7
	v_mov_b32_e32 v66, v4
	v_mov_b32_e32 v67, v5
	v_fma_f32 v6, v2, v4, v32
	v_fma_f32 v7, v2, v5, v33
	v_fma_f32 v6, -v3, v67, v6
	v_fma_f32 v7, v3, v66, v7
	v_mov_b32_e32 v4, v6
	v_mov_b32_e32 v5, v7
	v_mov_b32_e32 v68, v4
	v_mov_b32_e32 v69, v5
	v_fma_f32 v6, v2, v4, v34
	v_fma_f32 v7, v2, v5, v35
	v_fma_f32 v6, -v3, v69, v6
	v_fma_f32 v7, v3, v68, v7
	v_mov_b32_e32 v4, v6
	v_mov_b32_e32 v5, v7
	v_mov_b32_e32 v70, v4
	v_mov_b32_e32 v71, v5
	v_fma_f32 v6, v2, v4, v36
	v_fma_f32 v7, v2, v5, v37
	v_fma_f32 v6, -v3, v71, v6
	v_fma_f32 v7, v3, v70, v7
	v_mov_b32_e32 v4, v6
	v_mov_b32_e32 v5, v7
	v_mov_b32_e32 v72, v4
	v_mov_b32_e32 v73, v5
	v_fma_f32 v6, v2, v4, v38
	v_fma_f32 v7, v2, v5, v39
	v_fma_f32 v6, -v3, v73, v6
	v_fma_f32 v7, v3, v72, v7
	v_mov_b32_e32 v4, v6
	v_mov_b32_e32 v5, v7
	v_mov_b32_e32 v74, v4
	v_mov_b32_e32 v75, v5
	v_fma_f32 v6, v2, v4, v40
	v_fma_f32 v7, v2, v5, v41
	v_fma_f32 v6, -v3, v75, v6
	v_fma_f32 v7, v3, v74, v7
	v_mov_b32_e32 v4, v6
	v_mov_b32_e32 v5, v7
	v_mov_b32_e32 v76, v4
	v_mov_b32_e32 v77, v5
	v_fma_f32 v6, v2, v4, v42
	v_fma_f32 v7, v2, v5, v43
	v_fma_f32 v6, -v3, v77, v6
	v_fma_f32 v7, v3, v76, v7
	v_mov_b32_e32 v4, v6
	v_mov_b32_e32 v5, v7
	v_mov_b32_e32 v78, v4
	v_mov_b32_e32 v79, v5
	v_fma_f32 v6, v2, v4, v44
	v_fma_f32 v7, v2, v5, v45
	v_fma_f32 v6, -v3, v79, v6
	v_fma_f32 v7, v3, v78, v7
	v_mov_b32_e32 v4, v6
	v_mov_b32_e32 v5, v7
	v_mov_b32_e32 v80, v4
	v_mov_b32_e32 v81, v5
	v_fma_f32 v6, v2, v4, v46
	v_fma_f32 v7, v2, v5, v47
	v_fma_f32 v6, -v3, v81, v6
	v_fma_f32 v7, v3, v80, v7
	v_mov_b32_e32 v4, v6
	v_mov_b32_e32 v5, v7
	v_mov_b32_e32 v82, v4
	v_mov_b32_e32 v83, v5
	v_fma_f32 v6, v2, v4, v48
	v_fma_f32 v7, v2, v5, v49
	v_fma_f32 v6, -v3, v83, v6
	v_fma_f32 v7, v3, v82, v7
	v_mov_b32_e32 v4, v6
	v_mov_b32_e32 v5, v7
	v_mov_b32_e32 v84, v4
	v_mov_b32_e32 v85, v5
	v_fma_f32 v6, v2, v4, v50
	v_fma_f32 v7, v2, v5, v51
	v_fma_f32 v6, -v3, v85, v6
	v_fma_f32 v7, v3, v84, v7
	v_mov_b32_e32 v4, v6
	v_mov_b32_e32 v5, v7
	s_cmp_eq_u32 s22, 16
	s_cbranch_scc1 .Lp7_scan_done
	v_mov_b32_e32 v86, v4
	v_mov_b32_e32 v87, v5
	v_fma_f32 v6, v2, v4, v52
	v_fma_f32 v7, v2, v5, v53
	v_fma_f32 v6, -v3, v87, v6
	v_fma_f32 v7, v3, v86, v7
	v_mov_b32_e32 v4, v6
	v_mov_b32_e32 v5, v7
.Lp7_scan_done:
	s_lshl_b32 s10, s95, 9
	v_add_u32_e32 v16, s10, v0
	v_mov_b32_e32 v6, v4
	v_mov_b32_e32 v7, v5
	ds_write_b64 v16, v[6:7]
	v_mul_f32_e32 v8, v2, v2
	v_mul_f32_e32 v9, v2, v3
	v_fma_f32 v8, -v3, v3, v8
	v_fma_f32 v9, v3, v2, v9
	v_mul_f32_e32 v10, v8, v8
	v_mul_f32_e32 v11, v8, v9
	v_fma_f32 v10, -v9, v9, v10
	v_fma_f32 v11, v9, v8, v11
	v_mov_b32_e32 v8, v10
	v_mov_b32_e32 v9, v11
	v_mul_f32_e32 v10, v8, v8
	v_mul_f32_e32 v11, v8, v9
	v_fma_f32 v10, -v9, v9, v10
	v_fma_f32 v11, v9, v8, v11
	v_mov_b32_e32 v8, v10
	v_mov_b32_e32 v9, v11
	v_mul_f32_e32 v10, v8, v8
	v_mul_f32_e32 v11, v8, v9
	v_fma_f32 v10, -v9, v9, v10
	v_fma_f32 v11, v9, v8, v11
	v_mov_b32_e32 v8, v10
	v_mov_b32_e32 v9, v11
	v_mul_f32_e32 v10, v8, v2
	v_mul_f32_e32 v11, v8, v3
	v_fma_f32 v10, -v9, v3, v10
	v_fma_f32 v11, v9, v2, v11
	s_waitcnt lgkmcnt(0)
	s_barrier
	v_mov_b32_e32 v12, 0
	v_mov_b32_e32 v13, 0
	s_cmp_le_u32 s95, 0
	s_cbranch_scc1 .Lp7_carry_done
	ds_read_b64 v[18:19], v0 offset:0
	v_mul_f32_e32 v6, v10, v12
	v_mul_f32_e32 v7, v10, v13
	v_fma_f32 v6, -v11, v13, v6
	v_fma_f32 v7, v11, v12, v7
	s_waitcnt lgkmcnt(0)
	v_add_f32_e32 v12, v6, v18
	v_add_f32_e32 v13, v7, v19
	s_cmp_le_u32 s95, 1
	s_cbranch_scc1 .Lp7_carry_done
	ds_read_b64 v[18:19], v0 offset:512
	v_mul_f32_e32 v6, v10, v12
	v_mul_f32_e32 v7, v10, v13
	v_fma_f32 v6, -v11, v13, v6
	v_fma_f32 v7, v11, v12, v7
	s_waitcnt lgkmcnt(0)
	v_add_f32_e32 v12, v6, v18
	v_add_f32_e32 v13, v7, v19
	s_cmp_le_u32 s95, 2
	s_cbranch_scc1 .Lp7_carry_done
	ds_read_b64 v[18:19], v0 offset:1024
	v_mul_f32_e32 v6, v10, v12
	v_mul_f32_e32 v7, v10, v13
	v_fma_f32 v6, -v11, v13, v6
	v_fma_f32 v7, v11, v12, v7
	s_waitcnt lgkmcnt(0)
	v_add_f32_e32 v12, v6, v18
	v_add_f32_e32 v13, v7, v19
	s_cmp_le_u32 s95, 3
	s_cbranch_scc1 .Lp7_carry_done
	ds_read_b64 v[18:19], v0 offset:1536
	v_mul_f32_e32 v6, v10, v12
	v_mul_f32_e32 v7, v10, v13
	v_fma_f32 v6, -v11, v13, v6
	v_fma_f32 v7, v11, v12, v7
	s_waitcnt lgkmcnt(0)
	v_add_f32_e32 v12, v6, v18
	v_add_f32_e32 v13, v7, v19
	s_cmp_le_u32 s95, 4
	s_cbranch_scc1 .Lp7_carry_done
	ds_read_b64 v[18:19], v0 offset:2048
	v_mul_f32_e32 v6, v8, v12
	v_mul_f32_e32 v7, v8, v13
	v_fma_f32 v6, -v9, v13, v6
	v_fma_f32 v7, v9, v12, v7
	s_waitcnt lgkmcnt(0)
	v_add_f32_e32 v12, v6, v18
	v_add_f32_e32 v13, v7, v19
	s_cmp_le_u32 s95, 5
	s_cbranch_scc1 .Lp7_carry_done
	ds_read_b64 v[18:19], v0 offset:2560
	v_mul_f32_e32 v6, v8, v12
	v_mul_f32_e32 v7, v8, v13
	v_fma_f32 v6, -v9, v13, v6
	v_fma_f32 v7, v9, v12, v7
	s_waitcnt lgkmcnt(0)
	v_add_f32_e32 v12, v6, v18
	v_add_f32_e32 v13, v7, v19
	s_cmp_le_u32 s95, 6
	s_cbranch_scc1 .Lp7_carry_done
	ds_read_b64 v[18:19], v0 offset:3072
	v_mul_f32_e32 v6, v8, v12
	v_mul_f32_e32 v7, v8, v13
	v_fma_f32 v6, -v9, v13, v6
	v_fma_f32 v7, v9, v12, v7
	s_waitcnt lgkmcnt(0)
	v_add_f32_e32 v12, v6, v18
	v_add_f32_e32 v13, v7, v19
.Lp7_carry_done:
	v_mov_b32_e32 v14, 1.0
	v_mov_b32_e32 v15, 0
	v_fma_f32 v88, v14, v12, v54
	v_fma_f32 v89, v14, v13, v55
	v_fma_f32 v88, -v15, v13, v88
	v_fma_f32 v89, v15, v12, v89
	s_add_i32 s25, s20, 0
	s_cmp_eq_u32 s5, 0
	s_cbranch_scc1 .Lp7_c100
	s_sub_i32 s27, 3, s25
	s_sub_i32 s10, 0x87, s25
	s_cmp_lt_u32 s25, 4
	s_cselect_b32 s27, s27, s10
	s_branch .Lp7_d100

.Lp7_d100:
	s_lshl_b32 s10, s27, 15
	s_add_u32 s46, s14, s10
	s_addc_u32 s47, s15, 0
	global_store_dwordx2 v0, v[88:89], s[46:47]
	v_mul_f32_e32 v6, v14, v2
	v_mul_f32_e32 v7, v14, v3
	v_fma_f32 v6, -v15, v3, v6
	v_fma_f32 v7, v15, v2, v7
	v_mov_b32_e32 v14, v6
	v_mov_b32_e32 v15, v7
	v_fma_f32 v88, v14, v12, v56
	v_fma_f32 v89, v14, v13, v57
	v_fma_f32 v88, -v15, v13, v88
	v_fma_f32 v89, v15, v12, v89
	s_add_i32 s25, s20, 1
	s_cmp_eq_u32 s5, 0
	s_cbranch_scc1 .Lp7_c101
	s_sub_i32 s27, 3, s25
	s_sub_i32 s10, 0x87, s25
	s_cmp_lt_u32 s25, 4
	s_cselect_b32 s27, s27, s10
	s_branch .Lp7_d101

.Lp7_d101:
	s_lshl_b32 s10, s27, 15
	s_add_u32 s46, s14, s10
	s_addc_u32 s47, s15, 0
	global_store_dwordx2 v0, v[88:89], s[46:47]
	v_mul_f32_e32 v6, v14, v2
	v_mul_f32_e32 v7, v14, v3
	v_fma_f32 v6, -v15, v3, v6
	v_fma_f32 v7, v15, v2, v7
	v_mov_b32_e32 v14, v6
	v_mov_b32_e32 v15, v7
	v_fma_f32 v88, v14, v12, v58
	v_fma_f32 v89, v14, v13, v59
	v_fma_f32 v88, -v15, v13, v88
	v_fma_f32 v89, v15, v12, v89
	s_add_i32 s25, s20, 2
	s_cmp_eq_u32 s5, 0
	s_cbranch_scc1 .Lp7_c102
	s_sub_i32 s27, 3, s25
	s_sub_i32 s10, 0x87, s25
	s_cmp_lt_u32 s25, 4
	s_cselect_b32 s27, s27, s10
	s_branch .Lp7_d102

.Lp7_d102:
	s_lshl_b32 s10, s27, 15
	s_add_u32 s46, s14, s10
	s_addc_u32 s47, s15, 0
	global_store_dwordx2 v0, v[88:89], s[46:47]
	v_mul_f32_e32 v6, v14, v2
	v_mul_f32_e32 v7, v14, v3
	v_fma_f32 v6, -v15, v3, v6
	v_fma_f32 v7, v15, v2, v7
	v_mov_b32_e32 v14, v6
	v_mov_b32_e32 v15, v7
	v_fma_f32 v88, v14, v12, v60
	v_fma_f32 v89, v14, v13, v61
	v_fma_f32 v88, -v15, v13, v88
	v_fma_f32 v89, v15, v12, v89
	s_add_i32 s25, s20, 3
	s_cmp_eq_u32 s5, 0
	s_cbranch_scc1 .Lp7_c103
	s_sub_i32 s27, 3, s25
	s_sub_i32 s10, 0x87, s25
	s_cmp_lt_u32 s25, 4
	s_cselect_b32 s27, s27, s10
	s_branch .Lp7_d103

.Lp7_d103:
	s_lshl_b32 s10, s27, 15
	s_add_u32 s46, s14, s10
	s_addc_u32 s47, s15, 0
	global_store_dwordx2 v0, v[88:89], s[46:47]
	v_mul_f32_e32 v6, v14, v2
	v_mul_f32_e32 v7, v14, v3
	v_fma_f32 v6, -v15, v3, v6
	v_fma_f32 v7, v15, v2, v7
	v_mov_b32_e32 v14, v6
	v_mov_b32_e32 v15, v7
	v_fma_f32 v88, v14, v12, v62
	v_fma_f32 v89, v14, v13, v63
	v_fma_f32 v88, -v15, v13, v88
	v_fma_f32 v89, v15, v12, v89
	s_add_i32 s25, s20, 4
	s_cmp_eq_u32 s5, 0
	s_cbranch_scc1 .Lp7_c104
	s_sub_i32 s27, 3, s25
	s_sub_i32 s10, 0x87, s25
	s_cmp_lt_u32 s25, 4
	s_cselect_b32 s27, s27, s10
	s_branch .Lp7_d104

.Lp7_d104:
	s_lshl_b32 s10, s27, 15
	s_add_u32 s46, s14, s10
	s_addc_u32 s47, s15, 0
	global_store_dwordx2 v0, v[88:89], s[46:47]
	v_mul_f32_e32 v6, v14, v2
	v_mul_f32_e32 v7, v14, v3
	v_fma_f32 v6, -v15, v3, v6
	v_fma_f32 v7, v15, v2, v7
	v_mov_b32_e32 v14, v6
	v_mov_b32_e32 v15, v7
	v_fma_f32 v88, v14, v12, v64
	v_fma_f32 v89, v14, v13, v65
	v_fma_f32 v88, -v15, v13, v88
	v_fma_f32 v89, v15, v12, v89
	s_add_i32 s25, s20, 5
	s_cmp_eq_u32 s5, 0
	s_cbranch_scc1 .Lp7_c105
	s_sub_i32 s27, 3, s25
	s_sub_i32 s10, 0x87, s25
	s_cmp_lt_u32 s25, 4
	s_cselect_b32 s27, s27, s10
	s_branch .Lp7_d105

.Lp7_d105:
	s_lshl_b32 s10, s27, 15
	s_add_u32 s46, s14, s10
	s_addc_u32 s47, s15, 0
	global_store_dwordx2 v0, v[88:89], s[46:47]
	v_mul_f32_e32 v6, v14, v2
	v_mul_f32_e32 v7, v14, v3
	v_fma_f32 v6, -v15, v3, v6
	v_fma_f32 v7, v15, v2, v7
	v_mov_b32_e32 v14, v6
	v_mov_b32_e32 v15, v7
	v_fma_f32 v88, v14, v12, v66
	v_fma_f32 v89, v14, v13, v67
	v_fma_f32 v88, -v15, v13, v88
	v_fma_f32 v89, v15, v12, v89
	s_add_i32 s25, s20, 6
	s_cmp_eq_u32 s5, 0
	s_cbranch_scc1 .Lp7_c106
	s_sub_i32 s27, 3, s25
	s_sub_i32 s10, 0x87, s25
	s_cmp_lt_u32 s25, 4
	s_cselect_b32 s27, s27, s10
	s_branch .Lp7_d106

.Lp7_d106:
	s_lshl_b32 s10, s27, 15
	s_add_u32 s46, s14, s10
	s_addc_u32 s47, s15, 0
	global_store_dwordx2 v0, v[88:89], s[46:47]
	v_mul_f32_e32 v6, v14, v2
	v_mul_f32_e32 v7, v14, v3
	v_fma_f32 v6, -v15, v3, v6
	v_fma_f32 v7, v15, v2, v7
	v_mov_b32_e32 v14, v6
	v_mov_b32_e32 v15, v7
	v_fma_f32 v88, v14, v12, v68
	v_fma_f32 v89, v14, v13, v69
	v_fma_f32 v88, -v15, v13, v88
	v_fma_f32 v89, v15, v12, v89
	s_add_i32 s25, s20, 7
	s_cmp_eq_u32 s5, 0
	s_cbranch_scc1 .Lp7_c107
	s_sub_i32 s27, 3, s25
	s_sub_i32 s10, 0x87, s25
	s_cmp_lt_u32 s25, 4
	s_cselect_b32 s27, s27, s10
	s_branch .Lp7_d107

.Lp7_d107:
	s_lshl_b32 s10, s27, 15
	s_add_u32 s46, s14, s10
	s_addc_u32 s47, s15, 0
	global_store_dwordx2 v0, v[88:89], s[46:47]
	v_mul_f32_e32 v6, v14, v2
	v_mul_f32_e32 v7, v14, v3
	v_fma_f32 v6, -v15, v3, v6
	v_fma_f32 v7, v15, v2, v7
	v_mov_b32_e32 v14, v6
	v_mov_b32_e32 v15, v7
	v_fma_f32 v88, v14, v12, v70
	v_fma_f32 v89, v14, v13, v71
	v_fma_f32 v88, -v15, v13, v88
	v_fma_f32 v89, v15, v12, v89
	s_add_i32 s25, s20, 8
	s_cmp_eq_u32 s5, 0
	s_cbranch_scc1 .Lp7_c108
	s_sub_i32 s27, 3, s25
	s_sub_i32 s10, 0x87, s25
	s_cmp_lt_u32 s25, 4
	s_cselect_b32 s27, s27, s10
	s_branch .Lp7_d108

.Lp7_d108:
	s_lshl_b32 s10, s27, 15
	s_add_u32 s46, s14, s10
	s_addc_u32 s47, s15, 0
	global_store_dwordx2 v0, v[88:89], s[46:47]
	v_mul_f32_e32 v6, v14, v2
	v_mul_f32_e32 v7, v14, v3
	v_fma_f32 v6, -v15, v3, v6
	v_fma_f32 v7, v15, v2, v7
	v_mov_b32_e32 v14, v6
	v_mov_b32_e32 v15, v7
	v_fma_f32 v88, v14, v12, v72
	v_fma_f32 v89, v14, v13, v73
	v_fma_f32 v88, -v15, v13, v88
	v_fma_f32 v89, v15, v12, v89
	s_add_i32 s25, s20, 9
	s_cmp_eq_u32 s5, 0
	s_cbranch_scc1 .Lp7_c109
	s_sub_i32 s27, 3, s25
	s_sub_i32 s10, 0x87, s25
	s_cmp_lt_u32 s25, 4
	s_cselect_b32 s27, s27, s10
	s_branch .Lp7_d109

.Lp7_d109:
	s_lshl_b32 s10, s27, 15
	s_add_u32 s46, s14, s10
	s_addc_u32 s47, s15, 0
	global_store_dwordx2 v0, v[88:89], s[46:47]
	v_mul_f32_e32 v6, v14, v2
	v_mul_f32_e32 v7, v14, v3
	v_fma_f32 v6, -v15, v3, v6
	v_fma_f32 v7, v15, v2, v7
	v_mov_b32_e32 v14, v6
	v_mov_b32_e32 v15, v7
	v_fma_f32 v88, v14, v12, v74
	v_fma_f32 v89, v14, v13, v75
	v_fma_f32 v88, -v15, v13, v88
	v_fma_f32 v89, v15, v12, v89
	s_add_i32 s25, s20, 10
	s_cmp_eq_u32 s5, 0
	s_cbranch_scc1 .Lp7_c110
	s_sub_i32 s27, 3, s25
	s_sub_i32 s10, 0x87, s25
	s_cmp_lt_u32 s25, 4
	s_cselect_b32 s27, s27, s10
	s_branch .Lp7_d110

.Lp7_d110:
	s_lshl_b32 s10, s27, 15
	s_add_u32 s46, s14, s10
	s_addc_u32 s47, s15, 0
	global_store_dwordx2 v0, v[88:89], s[46:47]
	v_mul_f32_e32 v6, v14, v2
	v_mul_f32_e32 v7, v14, v3
	v_fma_f32 v6, -v15, v3, v6
	v_fma_f32 v7, v15, v2, v7
	v_mov_b32_e32 v14, v6
	v_mov_b32_e32 v15, v7
	v_fma_f32 v88, v14, v12, v76
	v_fma_f32 v89, v14, v13, v77
	v_fma_f32 v88, -v15, v13, v88
	v_fma_f32 v89, v15, v12, v89
	s_add_i32 s25, s20, 11
	s_cmp_eq_u32 s5, 0
	s_cbranch_scc1 .Lp7_c111
	s_sub_i32 s27, 3, s25
	s_sub_i32 s10, 0x87, s25
	s_cmp_lt_u32 s25, 4
	s_cselect_b32 s27, s27, s10
	s_branch .Lp7_d111

.Lp7_d111:
	s_lshl_b32 s10, s27, 15
	s_add_u32 s46, s14, s10
	s_addc_u32 s47, s15, 0
	global_store_dwordx2 v0, v[88:89], s[46:47]
	v_mul_f32_e32 v6, v14, v2
	v_mul_f32_e32 v7, v14, v3
	v_fma_f32 v6, -v15, v3, v6
	v_fma_f32 v7, v15, v2, v7
	v_mov_b32_e32 v14, v6
	v_mov_b32_e32 v15, v7
	v_fma_f32 v88, v14, v12, v78
	v_fma_f32 v89, v14, v13, v79
	v_fma_f32 v88, -v15, v13, v88
	v_fma_f32 v89, v15, v12, v89
	s_add_i32 s25, s20, 12
	s_cmp_eq_u32 s5, 0
	s_cbranch_scc1 .Lp7_c112
	s_sub_i32 s27, 3, s25
	s_sub_i32 s10, 0x87, s25
	s_cmp_lt_u32 s25, 4
	s_cselect_b32 s27, s27, s10
	s_branch .Lp7_d112

.Lp7_d112:
	s_lshl_b32 s10, s27, 15
	s_add_u32 s46, s14, s10
	s_addc_u32 s47, s15, 0
	global_store_dwordx2 v0, v[88:89], s[46:47]
	v_mul_f32_e32 v6, v14, v2
	v_mul_f32_e32 v7, v14, v3
	v_fma_f32 v6, -v15, v3, v6
	v_fma_f32 v7, v15, v2, v7
	v_mov_b32_e32 v14, v6
	v_mov_b32_e32 v15, v7
	v_fma_f32 v88, v14, v12, v80
	v_fma_f32 v89, v14, v13, v81
	v_fma_f32 v88, -v15, v13, v88
	v_fma_f32 v89, v15, v12, v89
	s_add_i32 s25, s20, 13
	s_cmp_eq_u32 s5, 0
	s_cbranch_scc1 .Lp7_c113
	s_sub_i32 s27, 3, s25
	s_sub_i32 s10, 0x87, s25
	s_cmp_lt_u32 s25, 4
	s_cselect_b32 s27, s27, s10
	s_branch .Lp7_d113

.Lp7_d113:
	s_lshl_b32 s10, s27, 15
	s_add_u32 s46, s14, s10
	s_addc_u32 s47, s15, 0
	global_store_dwordx2 v0, v[88:89], s[46:47]
	v_mul_f32_e32 v6, v14, v2
	v_mul_f32_e32 v7, v14, v3
	v_fma_f32 v6, -v15, v3, v6
	v_fma_f32 v7, v15, v2, v7
	v_mov_b32_e32 v14, v6
	v_mov_b32_e32 v15, v7
	v_fma_f32 v88, v14, v12, v82
	v_fma_f32 v89, v14, v13, v83
	v_fma_f32 v88, -v15, v13, v88
	v_fma_f32 v89, v15, v12, v89
	s_add_i32 s25, s20, 14
	s_cmp_eq_u32 s5, 0
	s_cbranch_scc1 .Lp7_c114
	s_sub_i32 s27, 3, s25
	s_sub_i32 s10, 0x87, s25
	s_cmp_lt_u32 s25, 4
	s_cselect_b32 s27, s27, s10
	s_branch .Lp7_d114

.Lp7_d114:
	s_lshl_b32 s10, s27, 15
	s_add_u32 s46, s14, s10
	s_addc_u32 s47, s15, 0
	global_store_dwordx2 v0, v[88:89], s[46:47]
	v_mul_f32_e32 v6, v14, v2
	v_mul_f32_e32 v7, v14, v3
	v_fma_f32 v6, -v15, v3, v6
	v_fma_f32 v7, v15, v2, v7
	v_mov_b32_e32 v14, v6
	v_mov_b32_e32 v15, v7
	v_fma_f32 v88, v14, v12, v84
	v_fma_f32 v89, v14, v13, v85
	v_fma_f32 v88, -v15, v13, v88
	v_fma_f32 v89, v15, v12, v89
	s_add_i32 s25, s20, 15
	s_cmp_eq_u32 s5, 0
	s_cbranch_scc1 .Lp7_c115
	s_sub_i32 s27, 3, s25
	s_sub_i32 s10, 0x87, s25
	s_cmp_lt_u32 s25, 4
	s_cselect_b32 s27, s27, s10
	s_branch .Lp7_d115

.Lp7_d115:
	s_lshl_b32 s10, s27, 15
	s_add_u32 s46, s14, s10
	s_addc_u32 s47, s15, 0
	global_store_dwordx2 v0, v[88:89], s[46:47]
	v_mul_f32_e32 v6, v14, v2
	v_mul_f32_e32 v7, v14, v3
	v_fma_f32 v6, -v15, v3, v6
	v_fma_f32 v7, v15, v2, v7
	v_mov_b32_e32 v14, v6
	v_mov_b32_e32 v15, v7
	s_cmp_eq_u32 s22, 16
	s_cbranch_scc1 .Lp7_st_done
	v_fma_f32 v88, v14, v12, v86
	v_fma_f32 v89, v14, v13, v87
	v_fma_f32 v88, -v15, v13, v88
	v_fma_f32 v89, v15, v12, v89
	s_add_i32 s25, s20, 16
	s_cmp_eq_u32 s5, 0
	s_cbranch_scc1 .Lp7_c116
	s_sub_i32 s27, 3, s25
	s_sub_i32 s10, 0x87, s25
	s_cmp_lt_u32 s25, 4
	s_cselect_b32 s27, s27, s10
	s_branch .Lp7_d116

.Lp7_d116:
	s_lshl_b32 s10, s27, 15
	s_add_u32 s46, s14, s10
	s_addc_u32 s47, s15, 0
	global_store_dwordx2 v0, v[88:89], s[46:47]
.Lp7_st_done:
	s_barrier
	s_add_i32 s4, s4, s9
	s_cmpk_gt_u32 s4, 0xff
	s_cbranch_scc0 .Lp7_chain
.Lp7_done:
.LBB0_596:
	s_cmp_gt_i32 s91, 8
	s_cselect_b64 s[2:3], -1, 0
	s_and_b64 s[0:1], s[0:1], s[2:3]
	s_andn2_b64 vcc, exec, s[0:1]
	s_cbranch_vccnz .LBB0_650
	s_waitcnt vmcnt(0)
	s_waitcnt lgkmcnt(0)
	s_barrier
	s_and_saveexec_b64 s[0:1], s[92:93]
	s_cbranch_execz .LBB0_649
	s_add_i32 s4, 0, 0x27ff0
	v_mov_b32_e32 v0, s4
	s_waitcnt vmcnt(0) expcnt(0) lgkmcnt(0)
	ds_read_b32 v2, v0
	s_add_i32 s4, 0, 0x27ff4
	v_mov_b32_e32 v0, s4
	ds_read_b32 v0, v0
	s_waitcnt lgkmcnt(1)
	v_cmp_ne_u32_e32 vcc, 0, v2
	s_cbranch_vccnz .LBB0_613
	s_add_u32 s4, s30, 0x38200
	s_addc_u32 s5, s31, 0
	s_add_u32 s6, s30, 0x38400
	s_addc_u32 s7, s31, 0
	s_add_u32 s10, s30, 0x38500
	s_addc_u32 s11, s31, 0
	s_add_u32 s12, s30, 0x38600
	s_addc_u32 s13, s31, 0
	s_add_u32 s14, s30, 0x38700
	s_addc_u32 s15, s31, 0
	s_add_u32 s16, s30, 0x38800
	s_addc_u32 s17, s31, 0
	s_add_u32 s18, s30, 0x38900
	s_addc_u32 s19, s31, 0
	s_add_u32 s20, s30, 0x38a00
	s_addc_u32 s21, s31, 0
	s_add_u32 s22, s30, 0x38b00
	s_addc_u32 s23, s31, 0
	s_add_u32 s24, s30, 0x38c00
	s_addc_u32 s25, s31, 0
	s_add_u32 s26, s30, 0x38d00
	s_addc_u32 s27, s31, 0
	s_add_u32 s34, s30, 0x38e00
	s_addc_u32 s35, s31, 0
	s_add_u32 s40, s30, 0x38f00
	s_addc_u32 s41, s31, 0
	s_add_u32 s44, s30, 0x39000
	s_addc_u32 s45, s31, 0
	s_add_u32 s46, s30, 0x39100
	s_addc_u32 s47, s31, 0
	s_add_u32 s48, s30, 0x39200
	s_addc_u32 s49, s31, 0
	s_mul_i32 s33, s89, s9
	s_add_u32 s54, s30, 0x39300
	s_mul_i32 s33, s33, s88
	s_addc_u32 s55, s31, 0
	s_mov_b32 s62, 1
	v_mov_b32_e32 v16, 0
	s_branch .LBB0_601
